# v088 plus the same four-rows-per-trip edit in the standalone finalize-C row loop
# baseline (speedup 1.0000x reference)
; __device__ __forceinline__ float bf2f(bfu h) { return __uint_as_float(((unsigned)h) << 16); }
; __device__ __forceinline__ unsigned pack2(float a, float b) { return (unsigned)f2bf(a) | ((unsigned)f2bf(b) << 16); }
; __device__ __forceinline__ float frsq(float x) { return __builtin_amdgcn_rsqf(x); }
; __device__ __forceinline__ float sigmoidf_(float x) { return frcp(1.0f + fexp(-x)); }
; #define SHX(v, m) shx_((v), (m), lane)
; __device__ void cd_fin_rows(const Params& p, int L, int row0, int nrows, const bool doC, const bool doD) {
;     ...
;   for (int rr = wid; rr < nrows; rr += 8) {
;     const long row = row0 + rr;
;     bfu* pr = buf + row * 4608;
;     const int c0 = lane * 8;
;     if (doC) {
;     bf16x8 o = *(const bf16x8*)(pr + 3584 + c0);
;     bf16x8 hg = *(const bf16x8*)(pr + 1536 + 1536 + c0);
;     float of[8]; float ss = 0.f;
;     for (int e = 0; e < 8; ++e) { of[e] = bf2f((bfu)o[e]); ss += of[e] * of[e]; }
;     ss += SHX(ss, 1); ss += SHX(ss, 2); ss += SHX(ss, 4); ss += SHX(ss, 8);
;     const float rs = frsq(ss * (1.0f / 128.0f) + 1e-6f);
;     float ra[8];
;     for (int e = 0; e < 8; ++e) ra[e] = of[e] * rs * p.hg_norm_g[li * 128 + ((c0 + e) & 127)] * sigmoidf_(bf2f((bfu)hg[e]));
;     uint4 wa; wa.x = pack2(ra[0], ra[1]); wa.y = pack2(ra[2], ra[3]); wa.z = pack2(ra[4], ra[5]); wa.w = pack2(ra[6], ra[7]);
;     *(uint4*)(pr + 1536 + c0) = wa;
;     }
.LBB0_33:
	v_lshl_add_u64 v[170:171], v[4:5], 0, s[26:27]
	v_lshl_add_u64 v[172:173], v[170:171], 0, s[26:27]
	v_lshl_add_u64 v[174:175], v[172:173], 0, s[26:27]
	global_load_dwordx4 v[10:13], v[4:5], off offset:-1024
	global_load_dwordx4 v[14:17], v[4:5], off
	global_load_dwordx4 v[18:21], v[2:3], off
	global_load_dwordx4 v[22:25], v[2:3], off offset:16
	global_load_dwordx4 v[50:53], v[170:171], off offset:-1024
	global_load_dwordx4 v[54:57], v[170:171], off
	global_load_dwordx4 v[58:61], v[2:3], off
	global_load_dwordx4 v[62:65], v[2:3], off offset:16
	global_load_dwordx4 v[90:93], v[172:173], off offset:-1024
	global_load_dwordx4 v[94:97], v[172:173], off
	global_load_dwordx4 v[98:101], v[2:3], off
	global_load_dwordx4 v[102:105], v[2:3], off offset:16
	global_load_dwordx4 v[130:133], v[174:175], off offset:-1024
	global_load_dwordx4 v[134:137], v[174:175], off
	global_load_dwordx4 v[138:141], v[2:3], off
	global_load_dwordx4 v[142:145], v[2:3], off offset:16
	v_add_u32_e32 v0, 32, v0
	v_cmp_lt_i32_e32 vcc, s21, v0
	s_or_b64 s[14:15], vcc, s[14:15]
	s_waitcnt vmcnt(12)
	v_lshlrev_b32_e32 v28, 16, v10
	v_and_b32_e32 v29, 0xffff0000, v10
	v_lshlrev_b32_e32 v30, 16, v11
	v_and_b32_e32 v31, 0xffff0000, v11
	v_lshlrev_b32_e32 v32, 16, v12
	v_and_b32_e32 v33, 0xffff0000, v12
	v_lshlrev_b32_e32 v34, 16, v13
	v_and_b32_e32 v35, 0xffff0000, v13
	v_lshlrev_b32_e32 v11, 16, v15
	v_lshlrev_b32_e32 v10, 16, v14
	v_and_b32_e32 v13, 0xffff0000, v15
	v_and_b32_e32 v12, 0xffff0000, v14
	v_mov_b32_e32 v26, v22
	v_mov_b32_e32 v27, v24
	v_mov_b32_e32 v24, v23
	v_mul_f32_e32 v36, 0xbfb8aa3b, v28
	v_mul_f32_e32 v37, 0xbfb8aa3b, v29
	v_pk_mul_f32 v[22:23], v[10:11], v[10:11]
	v_pk_mul_f32 v[28:29], v[12:13], v[12:13]
	v_mov_b32_e32 v14, v18
	v_lshlrev_b32_e32 v18, 16, v16
	v_and_b32_e32 v16, 0xffff0000, v16
	v_add_f32_e32 v22, v22, v28
	v_mul_f32_e32 v38, 0xbfb8aa3b, v30
	v_mul_f32_e32 v39, 0xbfb8aa3b, v31
	v_mov_b32_e32 v30, v16
	v_mov_b32_e32 v31, v18
	v_add_f32_e32 v22, v23, v22
	v_mov_b32_e32 v15, v20
	v_mov_b32_e32 v20, v19
	v_lshlrev_b32_e32 v19, 16, v17
	v_and_b32_e32 v17, 0xffff0000, v17
	v_pk_mul_f32 v[30:31], v[30:31], v[30:31]
	v_add_f32_e32 v22, v29, v22
	v_mul_f32_e32 v40, 0xbfb8aa3b, v32
	v_mul_f32_e32 v41, 0xbfb8aa3b, v33
	v_mov_b32_e32 v32, v17
	v_mov_b32_e32 v33, v19
	v_add_f32_e32 v22, v31, v22
	v_pk_mul_f32 v[32:33], v[32:33], v[32:33]
	v_add_f32_e32 v22, v30, v22
	v_add_f32_e32 v22, v33, v22
	v_add_f32_e32 v22, v32, v22
	ds_bpermute_b32 v23, v6, v22
	v_exp_f32_e32 v36, v36
	v_exp_f32_e32 v37, v37
	v_mul_f32_e32 v35, 0xbfb8aa3b, v35
	v_exp_f32_e32 v28, v41
	s_waitcnt lgkmcnt(0)
	v_add_f32_e32 v22, v22, v23
	ds_bpermute_b32 v23, v7, v22
	v_add_f32_e32 v31, 1.0, v36
	v_mul_f32_e32 v34, 0xbfb8aa3b, v34
	v_exp_f32_e32 v39, v39
	v_exp_f32_e32 v40, v40
	s_waitcnt lgkmcnt(0)
	v_add_f32_e32 v23, v22, v23
	ds_bpermute_b32 v36, v8, v23
	v_rcp_f32_e32 v22, v31
	v_exp_f32_e32 v30, v35
	v_exp_f32_e32 v38, v38
	v_exp_f32_e32 v29, v34
	s_waitcnt lgkmcnt(0)
	v_add_f32_e32 v31, v23, v36
	ds_bpermute_b32 v36, v9, v31
	v_add_f32_e32 v32, 1.0, v37
	v_add_f32_e32 v37, 1.0, v28
	v_rcp_f32_e32 v28, v32
	v_add_f32_e32 v34, 1.0, v39
	s_waitcnt lgkmcnt(0)
	v_add_f32_e32 v31, v31, v36
	v_fmamk_f32 v31, v31, 0x3c000000, v201
	v_rsq_f32_e32 v32, v31
	v_add_f32_e32 v35, 1.0, v40
	v_add_f32_e32 v39, 1.0, v30
	v_add_f32_e32 v33, 1.0, v38
	v_add_f32_e32 v38, 1.0, v29
	v_rcp_f32_e32 v29, v34
	v_rcp_f32_e32 v30, v35
	v_rcp_f32_e32 v34, v37
	v_rcp_f32_e32 v35, v39
	v_rcp_f32_e32 v23, v33
	v_rcp_f32_e32 v31, v38
	v_pk_mul_f32 v[12:13], v[32:33], v[12:13] op_sel_hi:[0,1]
	v_pk_mul_f32 v[16:17], v[32:33], v[16:17] op_sel_hi:[0,1]
	v_pk_mul_f32 v[10:11], v[32:33], v[10:11] op_sel_hi:[0,1]
	v_pk_mul_f32 v[18:19], v[32:33], v[18:19] op_sel_hi:[0,1]
	v_pk_mul_f32 v[12:13], v[20:21], v[12:13]
	v_pk_mul_f32 v[16:17], v[24:25], v[16:17]
	v_pk_mul_f32 v[10:11], v[14:15], v[10:11]
	v_pk_mul_f32 v[14:15], v[26:27], v[18:19]
	v_pk_mul_f32 v[12:13], v[28:29], v[12:13]
	v_pk_mul_f32 v[16:17], v[34:35], v[16:17]
	v_pk_mul_f32 v[10:11], v[22:23], v[10:11]
	v_pk_mul_f32 v[14:15], v[30:31], v[14:15]
	v_and_b32_sdwa v20, v13, v220 dst_sel:DWORD dst_unused:UNUSED_PAD src0_sel:WORD_1 src1_sel:DWORD
	v_and_b32_sdwa v21, v12, v220 dst_sel:DWORD dst_unused:UNUSED_PAD src0_sel:WORD_1 src1_sel:DWORD
	v_and_b32_sdwa v24, v17, v220 dst_sel:DWORD dst_unused:UNUSED_PAD src0_sel:WORD_1 src1_sel:DWORD
	v_and_b32_sdwa v25, v16, v220 dst_sel:DWORD dst_unused:UNUSED_PAD src0_sel:WORD_1 src1_sel:DWORD
	v_and_b32_sdwa v18, v11, v220 dst_sel:DWORD dst_unused:UNUSED_PAD src0_sel:WORD_1 src1_sel:DWORD
	v_and_b32_sdwa v19, v10, v220 dst_sel:DWORD dst_unused:UNUSED_PAD src0_sel:WORD_1 src1_sel:DWORD
	v_and_b32_sdwa v22, v15, v220 dst_sel:DWORD dst_unused:UNUSED_PAD src0_sel:WORD_1 src1_sel:DWORD
	v_and_b32_sdwa v23, v14, v220 dst_sel:DWORD dst_unused:UNUSED_PAD src0_sel:WORD_1 src1_sel:DWORD
	v_add3_u32 v13, v13, v20, s72
	v_add3_u32 v12, v12, v21, s72
	v_add3_u32 v17, v17, v24, s72
	v_add3_u32 v16, v16, v25, s72
	v_add3_u32 v10, v10, v19, s72
	v_add3_u32 v11, v11, v18, s72
	v_add3_u32 v14, v14, v23, s72
	v_add3_u32 v15, v15, v22, s72
	v_and_b32_e32 v13, 0xffff0000, v13
	v_and_b32_e32 v12, 0xffff0000, v12
	v_and_b32_e32 v17, 0xffff0000, v17
	v_and_b32_e32 v16, 0xffff0000, v16
	v_or_b32_sdwa v11, v13, v11 dst_sel:DWORD dst_unused:UNUSED_PAD src0_sel:DWORD src1_sel:WORD_1
	v_or_b32_sdwa v10, v12, v10 dst_sel:DWORD dst_unused:UNUSED_PAD src0_sel:DWORD src1_sel:WORD_1
	v_or_b32_sdwa v13, v17, v15 dst_sel:DWORD dst_unused:UNUSED_PAD src0_sel:DWORD src1_sel:WORD_1
	v_or_b32_sdwa v12, v16, v14 dst_sel:DWORD dst_unused:UNUSED_PAD src0_sel:DWORD src1_sel:WORD_1
	global_store_dwordx4 v[4:5], v[10:13], off offset:-4096
	s_waitcnt vmcnt(9)
; __device__ __forceinline__ float bf2f(bfu h) { return __uint_as_float(((unsigned)h) << 16); }
; __device__ __forceinline__ unsigned pack2(float a, float b) { return (unsigned)f2bf(a) | ((unsigned)f2bf(b) << 16); }
; __device__ __forceinline__ float frsq(float x) { return __builtin_amdgcn_rsqf(x); }
; __device__ __forceinline__ float sigmoidf_(float x) { return frcp(1.0f + fexp(-x)); }
; #define SHX(v, m) shx_((v), (m), lane)
; __device__ void cd_fin_rows(const Params& p, int L, int row0, int nrows, const bool doC, const bool doD) {
;     ...
;     if (doC) {
;     bf16x8 o = *(const bf16x8*)(pr + 3584 + c0);
;     bf16x8 hg = *(const bf16x8*)(pr + 1536 + 1536 + c0);
;     float of[8]; float ss = 0.f;
;     for (int e = 0; e < 8; ++e) { of[e] = bf2f((bfu)o[e]); ss += of[e] * of[e]; }
;     ss += SHX(ss, 1); ss += SHX(ss, 2); ss += SHX(ss, 4); ss += SHX(ss, 8);
;     const float rs = frsq(ss * (1.0f / 128.0f) + 1e-6f);
;     float ra[8];
;     for (int e = 0; e < 8; ++e) ra[e] = of[e] * rs * p.hg_norm_g[li * 128 + ((c0 + e) & 127)] * sigmoidf_(bf2f((bfu)hg[e]));
;     uint4 wa; wa.x = pack2(ra[0], ra[1]); wa.y = pack2(ra[2], ra[3]); wa.z = pack2(ra[4], ra[5]); wa.w = pack2(ra[6], ra[7]);
;     *(uint4*)(pr + 1536 + c0) = wa;
;     }
	v_lshlrev_b32_e32 v68, 16, v50
	v_and_b32_e32 v69, 0xffff0000, v50
	v_lshlrev_b32_e32 v70, 16, v51
	v_and_b32_e32 v71, 0xffff0000, v51
	v_lshlrev_b32_e32 v72, 16, v52
	v_and_b32_e32 v73, 0xffff0000, v52
	v_lshlrev_b32_e32 v74, 16, v53
	v_and_b32_e32 v75, 0xffff0000, v53
	v_lshlrev_b32_e32 v51, 16, v55
	v_lshlrev_b32_e32 v50, 16, v54
	v_and_b32_e32 v53, 0xffff0000, v55
	v_and_b32_e32 v52, 0xffff0000, v54
	v_mov_b32_e32 v66, v62
	v_mov_b32_e32 v67, v64
	v_mov_b32_e32 v64, v63
	v_mul_f32_e32 v76, 0xbfb8aa3b, v68
	v_mul_f32_e32 v77, 0xbfb8aa3b, v69
	v_pk_mul_f32 v[62:63], v[50:51], v[50:51]
	v_pk_mul_f32 v[68:69], v[52:53], v[52:53]
	v_mov_b32_e32 v54, v58
	v_lshlrev_b32_e32 v58, 16, v56
	v_and_b32_e32 v56, 0xffff0000, v56
	v_add_f32_e32 v62, v62, v68
	v_mul_f32_e32 v78, 0xbfb8aa3b, v70
	v_mul_f32_e32 v79, 0xbfb8aa3b, v71
	v_mov_b32_e32 v70, v56
	v_mov_b32_e32 v71, v58
	v_add_f32_e32 v62, v63, v62
	v_mov_b32_e32 v55, v60
	v_mov_b32_e32 v60, v59
	v_lshlrev_b32_e32 v59, 16, v57
	v_and_b32_e32 v57, 0xffff0000, v57
	v_pk_mul_f32 v[70:71], v[70:71], v[70:71]
	v_add_f32_e32 v62, v69, v62
	v_mul_f32_e32 v80, 0xbfb8aa3b, v72
	v_mul_f32_e32 v81, 0xbfb8aa3b, v73
	v_mov_b32_e32 v72, v57
	v_mov_b32_e32 v73, v59
	v_add_f32_e32 v62, v71, v62
	v_pk_mul_f32 v[72:73], v[72:73], v[72:73]
	v_add_f32_e32 v62, v70, v62
	v_add_f32_e32 v62, v73, v62
	v_add_f32_e32 v62, v72, v62
	ds_bpermute_b32 v63, v6, v62
	v_exp_f32_e32 v76, v76
	v_exp_f32_e32 v77, v77
	v_mul_f32_e32 v75, 0xbfb8aa3b, v75
	v_exp_f32_e32 v68, v81
	s_waitcnt lgkmcnt(0)
	v_add_f32_e32 v62, v62, v63
	ds_bpermute_b32 v63, v7, v62
	v_add_f32_e32 v71, 1.0, v76
	v_mul_f32_e32 v74, 0xbfb8aa3b, v74
	v_exp_f32_e32 v79, v79
	v_exp_f32_e32 v80, v80
	s_waitcnt lgkmcnt(0)
	v_add_f32_e32 v63, v62, v63
	ds_bpermute_b32 v76, v8, v63
	v_rcp_f32_e32 v62, v71
	v_exp_f32_e32 v70, v75
	v_exp_f32_e32 v78, v78
	v_exp_f32_e32 v69, v74
	s_waitcnt lgkmcnt(0)
	v_add_f32_e32 v71, v63, v76
	ds_bpermute_b32 v76, v9, v71
	v_add_f32_e32 v72, 1.0, v77
	v_add_f32_e32 v77, 1.0, v68
	v_rcp_f32_e32 v68, v72
	v_add_f32_e32 v74, 1.0, v79
	s_waitcnt lgkmcnt(0)
	v_add_f32_e32 v71, v71, v76
	v_fmamk_f32 v71, v71, 0x3c000000, v201
	v_rsq_f32_e32 v72, v71
	v_add_f32_e32 v75, 1.0, v80
	v_add_f32_e32 v79, 1.0, v70
	v_add_f32_e32 v73, 1.0, v78
	v_add_f32_e32 v78, 1.0, v69
	v_rcp_f32_e32 v69, v74
	v_rcp_f32_e32 v70, v75
	v_rcp_f32_e32 v74, v77
	v_rcp_f32_e32 v75, v79
	v_rcp_f32_e32 v63, v73
	v_rcp_f32_e32 v71, v78
	v_pk_mul_f32 v[52:53], v[72:73], v[52:53] op_sel_hi:[0,1]
	v_pk_mul_f32 v[56:57], v[72:73], v[56:57] op_sel_hi:[0,1]
	v_pk_mul_f32 v[50:51], v[72:73], v[50:51] op_sel_hi:[0,1]
	v_pk_mul_f32 v[58:59], v[72:73], v[58:59] op_sel_hi:[0,1]
	v_pk_mul_f32 v[52:53], v[60:61], v[52:53]
	v_pk_mul_f32 v[56:57], v[64:65], v[56:57]
	v_pk_mul_f32 v[50:51], v[54:55], v[50:51]
	v_pk_mul_f32 v[54:55], v[66:67], v[58:59]
	v_pk_mul_f32 v[52:53], v[68:69], v[52:53]
	v_pk_mul_f32 v[56:57], v[74:75], v[56:57]
	v_pk_mul_f32 v[50:51], v[62:63], v[50:51]
	v_pk_mul_f32 v[54:55], v[70:71], v[54:55]
	v_and_b32_sdwa v60, v53, v220 dst_sel:DWORD dst_unused:UNUSED_PAD src0_sel:WORD_1 src1_sel:DWORD
	v_and_b32_sdwa v61, v52, v220 dst_sel:DWORD dst_unused:UNUSED_PAD src0_sel:WORD_1 src1_sel:DWORD
	v_and_b32_sdwa v64, v57, v220 dst_sel:DWORD dst_unused:UNUSED_PAD src0_sel:WORD_1 src1_sel:DWORD
	v_and_b32_sdwa v65, v56, v220 dst_sel:DWORD dst_unused:UNUSED_PAD src0_sel:WORD_1 src1_sel:DWORD
	v_and_b32_sdwa v58, v51, v220 dst_sel:DWORD dst_unused:UNUSED_PAD src0_sel:WORD_1 src1_sel:DWORD
	v_and_b32_sdwa v59, v50, v220 dst_sel:DWORD dst_unused:UNUSED_PAD src0_sel:WORD_1 src1_sel:DWORD
	v_and_b32_sdwa v62, v55, v220 dst_sel:DWORD dst_unused:UNUSED_PAD src0_sel:WORD_1 src1_sel:DWORD
	v_and_b32_sdwa v63, v54, v220 dst_sel:DWORD dst_unused:UNUSED_PAD src0_sel:WORD_1 src1_sel:DWORD
	v_add3_u32 v53, v53, v60, s72
	v_add3_u32 v52, v52, v61, s72
	v_add3_u32 v57, v57, v64, s72
	v_add3_u32 v56, v56, v65, s72
	v_add3_u32 v50, v50, v59, s72
	v_add3_u32 v51, v51, v58, s72
	v_add3_u32 v54, v54, v63, s72
	v_add3_u32 v55, v55, v62, s72
	v_and_b32_e32 v53, 0xffff0000, v53
	v_and_b32_e32 v52, 0xffff0000, v52
	v_and_b32_e32 v57, 0xffff0000, v57
	v_and_b32_e32 v56, 0xffff0000, v56
	v_or_b32_sdwa v51, v53, v51 dst_sel:DWORD dst_unused:UNUSED_PAD src0_sel:DWORD src1_sel:WORD_1
	v_or_b32_sdwa v50, v52, v50 dst_sel:DWORD dst_unused:UNUSED_PAD src0_sel:DWORD src1_sel:WORD_1
	v_or_b32_sdwa v53, v57, v55 dst_sel:DWORD dst_unused:UNUSED_PAD src0_sel:DWORD src1_sel:WORD_1
	v_or_b32_sdwa v52, v56, v54 dst_sel:DWORD dst_unused:UNUSED_PAD src0_sel:DWORD src1_sel:WORD_1
	global_store_dwordx4 v[170:171], v[50:53], off offset:-4096
	s_waitcnt vmcnt(6)
	v_lshlrev_b32_e32 v108, 16, v90
	v_and_b32_e32 v109, 0xffff0000, v90
	v_lshlrev_b32_e32 v110, 16, v91
	v_and_b32_e32 v111, 0xffff0000, v91
	v_lshlrev_b32_e32 v112, 16, v92
	v_and_b32_e32 v113, 0xffff0000, v92
	v_lshlrev_b32_e32 v114, 16, v93
	v_and_b32_e32 v115, 0xffff0000, v93
	v_lshlrev_b32_e32 v91, 16, v95
	v_lshlrev_b32_e32 v90, 16, v94
	v_and_b32_e32 v93, 0xffff0000, v95
	v_and_b32_e32 v92, 0xffff0000, v94
	v_mov_b32_e32 v106, v102
	v_mov_b32_e32 v107, v104
	v_mov_b32_e32 v104, v103
	v_mul_f32_e32 v116, 0xbfb8aa3b, v108
	v_mul_f32_e32 v117, 0xbfb8aa3b, v109
	v_pk_mul_f32 v[102:103], v[90:91], v[90:91]
	v_pk_mul_f32 v[108:109], v[92:93], v[92:93]
	v_mov_b32_e32 v94, v98
	v_lshlrev_b32_e32 v98, 16, v96
	v_and_b32_e32 v96, 0xffff0000, v96
	v_add_f32_e32 v102, v102, v108
	v_mul_f32_e32 v118, 0xbfb8aa3b, v110
	v_mul_f32_e32 v119, 0xbfb8aa3b, v111
	v_mov_b32_e32 v110, v96
	v_mov_b32_e32 v111, v98
	v_add_f32_e32 v102, v103, v102
	v_mov_b32_e32 v95, v100
	v_mov_b32_e32 v100, v99
	v_lshlrev_b32_e32 v99, 16, v97
	v_and_b32_e32 v97, 0xffff0000, v97
	v_pk_mul_f32 v[110:111], v[110:111], v[110:111]
	v_add_f32_e32 v102, v109, v102
	v_mul_f32_e32 v120, 0xbfb8aa3b, v112
	v_mul_f32_e32 v121, 0xbfb8aa3b, v113
	v_mov_b32_e32 v112, v97
	v_mov_b32_e32 v113, v99
	v_add_f32_e32 v102, v111, v102
	v_pk_mul_f32 v[112:113], v[112:113], v[112:113]
	v_add_f32_e32 v102, v110, v102
	v_add_f32_e32 v102, v113, v102
	v_add_f32_e32 v102, v112, v102
	ds_bpermute_b32 v103, v6, v102
	v_exp_f32_e32 v116, v116
	v_exp_f32_e32 v117, v117
	v_mul_f32_e32 v115, 0xbfb8aa3b, v115
	v_exp_f32_e32 v108, v121
	s_waitcnt lgkmcnt(0)
; __device__ __forceinline__ float bf2f(bfu h) { return __uint_as_float(((unsigned)h) << 16); }
; __device__ __forceinline__ unsigned pack2(float a, float b) { return (unsigned)f2bf(a) | ((unsigned)f2bf(b) << 16); }
; __device__ __forceinline__ float frsq(float x) { return __builtin_amdgcn_rsqf(x); }
; __device__ __forceinline__ float sigmoidf_(float x) { return frcp(1.0f + fexp(-x)); }
; #define SHX(v, m) shx_((v), (m), lane)
; __device__ void cd_fin_rows(const Params& p, int L, int row0, int nrows, const bool doC, const bool doD) {
;     ...
;     if (doC) {
;     bf16x8 o = *(const bf16x8*)(pr + 3584 + c0);
;     bf16x8 hg = *(const bf16x8*)(pr + 1536 + 1536 + c0);
;     float of[8]; float ss = 0.f;
;     for (int e = 0; e < 8; ++e) { of[e] = bf2f((bfu)o[e]); ss += of[e] * of[e]; }
;     ss += SHX(ss, 1); ss += SHX(ss, 2); ss += SHX(ss, 4); ss += SHX(ss, 8);
;     const float rs = frsq(ss * (1.0f / 128.0f) + 1e-6f);
;     float ra[8];
;     for (int e = 0; e < 8; ++e) ra[e] = of[e] * rs * p.hg_norm_g[li * 128 + ((c0 + e) & 127)] * sigmoidf_(bf2f((bfu)hg[e]));
;     uint4 wa; wa.x = pack2(ra[0], ra[1]); wa.y = pack2(ra[2], ra[3]); wa.z = pack2(ra[4], ra[5]); wa.w = pack2(ra[6], ra[7]);
;     *(uint4*)(pr + 1536 + c0) = wa;
;     }
	v_add_f32_e32 v102, v102, v103
	ds_bpermute_b32 v103, v7, v102
	v_add_f32_e32 v111, 1.0, v116
	v_mul_f32_e32 v114, 0xbfb8aa3b, v114
	v_exp_f32_e32 v119, v119
	v_exp_f32_e32 v120, v120
	s_waitcnt lgkmcnt(0)
	v_add_f32_e32 v103, v102, v103
	ds_bpermute_b32 v116, v8, v103
	v_rcp_f32_e32 v102, v111
	v_exp_f32_e32 v110, v115
	v_exp_f32_e32 v118, v118
	v_exp_f32_e32 v109, v114
	s_waitcnt lgkmcnt(0)
	v_add_f32_e32 v111, v103, v116
	ds_bpermute_b32 v116, v9, v111
	v_add_f32_e32 v112, 1.0, v117
	v_add_f32_e32 v117, 1.0, v108
	v_rcp_f32_e32 v108, v112
	v_add_f32_e32 v114, 1.0, v119
	s_waitcnt lgkmcnt(0)
	v_add_f32_e32 v111, v111, v116
	v_fmamk_f32 v111, v111, 0x3c000000, v201
	v_rsq_f32_e32 v112, v111
	v_add_f32_e32 v115, 1.0, v120
	v_add_f32_e32 v119, 1.0, v110
	v_add_f32_e32 v113, 1.0, v118
	v_add_f32_e32 v118, 1.0, v109
	v_rcp_f32_e32 v109, v114
	v_rcp_f32_e32 v110, v115
	v_rcp_f32_e32 v114, v117
	v_rcp_f32_e32 v115, v119
	v_rcp_f32_e32 v103, v113
	v_rcp_f32_e32 v111, v118
	v_pk_mul_f32 v[92:93], v[112:113], v[92:93] op_sel_hi:[0,1]
	v_pk_mul_f32 v[96:97], v[112:113], v[96:97] op_sel_hi:[0,1]
	v_pk_mul_f32 v[90:91], v[112:113], v[90:91] op_sel_hi:[0,1]
	v_pk_mul_f32 v[98:99], v[112:113], v[98:99] op_sel_hi:[0,1]
	v_pk_mul_f32 v[92:93], v[100:101], v[92:93]
	v_pk_mul_f32 v[96:97], v[104:105], v[96:97]
	v_pk_mul_f32 v[90:91], v[94:95], v[90:91]
	v_pk_mul_f32 v[94:95], v[106:107], v[98:99]
	v_pk_mul_f32 v[92:93], v[108:109], v[92:93]
	v_pk_mul_f32 v[96:97], v[114:115], v[96:97]
	v_pk_mul_f32 v[90:91], v[102:103], v[90:91]
	v_pk_mul_f32 v[94:95], v[110:111], v[94:95]
	v_and_b32_sdwa v100, v93, v220 dst_sel:DWORD dst_unused:UNUSED_PAD src0_sel:WORD_1 src1_sel:DWORD
	v_and_b32_sdwa v101, v92, v220 dst_sel:DWORD dst_unused:UNUSED_PAD src0_sel:WORD_1 src1_sel:DWORD
	v_and_b32_sdwa v104, v97, v220 dst_sel:DWORD dst_unused:UNUSED_PAD src0_sel:WORD_1 src1_sel:DWORD
	v_and_b32_sdwa v105, v96, v220 dst_sel:DWORD dst_unused:UNUSED_PAD src0_sel:WORD_1 src1_sel:DWORD
	v_and_b32_sdwa v98, v91, v220 dst_sel:DWORD dst_unused:UNUSED_PAD src0_sel:WORD_1 src1_sel:DWORD
	v_and_b32_sdwa v99, v90, v220 dst_sel:DWORD dst_unused:UNUSED_PAD src0_sel:WORD_1 src1_sel:DWORD
	v_and_b32_sdwa v102, v95, v220 dst_sel:DWORD dst_unused:UNUSED_PAD src0_sel:WORD_1 src1_sel:DWORD
	v_and_b32_sdwa v103, v94, v220 dst_sel:DWORD dst_unused:UNUSED_PAD src0_sel:WORD_1 src1_sel:DWORD
	v_add3_u32 v93, v93, v100, s72
	v_add3_u32 v92, v92, v101, s72
	v_add3_u32 v97, v97, v104, s72
	v_add3_u32 v96, v96, v105, s72
	v_add3_u32 v90, v90, v99, s72
	v_add3_u32 v91, v91, v98, s72
	v_add3_u32 v94, v94, v103, s72
	v_add3_u32 v95, v95, v102, s72
	v_and_b32_e32 v93, 0xffff0000, v93
	v_and_b32_e32 v92, 0xffff0000, v92
	v_and_b32_e32 v97, 0xffff0000, v97
	v_and_b32_e32 v96, 0xffff0000, v96
	v_or_b32_sdwa v91, v93, v91 dst_sel:DWORD dst_unused:UNUSED_PAD src0_sel:DWORD src1_sel:WORD_1
	v_or_b32_sdwa v90, v92, v90 dst_sel:DWORD dst_unused:UNUSED_PAD src0_sel:DWORD src1_sel:WORD_1
	v_or_b32_sdwa v93, v97, v95 dst_sel:DWORD dst_unused:UNUSED_PAD src0_sel:DWORD src1_sel:WORD_1
	v_or_b32_sdwa v92, v96, v94 dst_sel:DWORD dst_unused:UNUSED_PAD src0_sel:DWORD src1_sel:WORD_1
	global_store_dwordx4 v[172:173], v[90:93], off offset:-4096
	s_waitcnt vmcnt(3)
	v_lshlrev_b32_e32 v148, 16, v130
	v_and_b32_e32 v149, 0xffff0000, v130
	v_lshlrev_b32_e32 v150, 16, v131
	v_and_b32_e32 v151, 0xffff0000, v131
	v_lshlrev_b32_e32 v152, 16, v132
	v_and_b32_e32 v153, 0xffff0000, v132
	v_lshlrev_b32_e32 v154, 16, v133
	v_and_b32_e32 v155, 0xffff0000, v133
	v_lshlrev_b32_e32 v131, 16, v135
	v_lshlrev_b32_e32 v130, 16, v134
	v_and_b32_e32 v133, 0xffff0000, v135
	v_and_b32_e32 v132, 0xffff0000, v134
	v_mov_b32_e32 v146, v142
	v_mov_b32_e32 v147, v144
	v_mov_b32_e32 v144, v143
	v_mul_f32_e32 v156, 0xbfb8aa3b, v148
	v_mul_f32_e32 v157, 0xbfb8aa3b, v149
	v_pk_mul_f32 v[142:143], v[130:131], v[130:131]
	v_pk_mul_f32 v[148:149], v[132:133], v[132:133]
	v_mov_b32_e32 v134, v138
	v_lshlrev_b32_e32 v138, 16, v136
	v_and_b32_e32 v136, 0xffff0000, v136
	v_add_f32_e32 v142, v142, v148
	v_mul_f32_e32 v158, 0xbfb8aa3b, v150
	v_mul_f32_e32 v159, 0xbfb8aa3b, v151
	v_mov_b32_e32 v150, v136
	v_mov_b32_e32 v151, v138
	v_add_f32_e32 v142, v143, v142
	v_mov_b32_e32 v135, v140
	v_mov_b32_e32 v140, v139
	v_lshlrev_b32_e32 v139, 16, v137
	v_and_b32_e32 v137, 0xffff0000, v137
	v_pk_mul_f32 v[150:151], v[150:151], v[150:151]
	v_add_f32_e32 v142, v149, v142
	v_mul_f32_e32 v160, 0xbfb8aa3b, v152
	v_mul_f32_e32 v161, 0xbfb8aa3b, v153
	v_mov_b32_e32 v152, v137
	v_mov_b32_e32 v153, v139
	v_add_f32_e32 v142, v151, v142
	v_pk_mul_f32 v[152:153], v[152:153], v[152:153]
	v_add_f32_e32 v142, v150, v142
	v_add_f32_e32 v142, v153, v142
	v_add_f32_e32 v142, v152, v142
	ds_bpermute_b32 v143, v6, v142
	v_exp_f32_e32 v156, v156
	v_exp_f32_e32 v157, v157
	v_mul_f32_e32 v155, 0xbfb8aa3b, v155
	v_exp_f32_e32 v148, v161
	s_waitcnt lgkmcnt(0)
; __device__ __forceinline__ float bf2f(bfu h) { return __uint_as_float(((unsigned)h) << 16); }
; __device__ __forceinline__ unsigned pack2(float a, float b) { return (unsigned)f2bf(a) | ((unsigned)f2bf(b) << 16); }
; __device__ __forceinline__ float frsq(float x) { return __builtin_amdgcn_rsqf(x); }
; __device__ __forceinline__ float sigmoidf_(float x) { return frcp(1.0f + fexp(-x)); }
; #define SHX(v, m) shx_((v), (m), lane)
; __device__ void cd_fin_rows(const Params& p, int L, int row0, int nrows, const bool doC, const bool doD) {
;     ...
;     if (doC) {
;     bf16x8 o = *(const bf16x8*)(pr + 3584 + c0);
;     bf16x8 hg = *(const bf16x8*)(pr + 1536 + 1536 + c0);
;     float of[8]; float ss = 0.f;
;     for (int e = 0; e < 8; ++e) { of[e] = bf2f((bfu)o[e]); ss += of[e] * of[e]; }
;     ss += SHX(ss, 1); ss += SHX(ss, 2); ss += SHX(ss, 4); ss += SHX(ss, 8);
;     const float rs = frsq(ss * (1.0f / 128.0f) + 1e-6f);
;     float ra[8];
;     for (int e = 0; e < 8; ++e) ra[e] = of[e] * rs * p.hg_norm_g[li * 128 + ((c0 + e) & 127)] * sigmoidf_(bf2f((bfu)hg[e]));
;     uint4 wa; wa.x = pack2(ra[0], ra[1]); wa.y = pack2(ra[2], ra[3]); wa.z = pack2(ra[4], ra[5]); wa.w = pack2(ra[6], ra[7]);
;     *(uint4*)(pr + 1536 + c0) = wa;
;     }
	v_add_f32_e32 v142, v142, v143
	ds_bpermute_b32 v143, v7, v142
	v_add_f32_e32 v151, 1.0, v156
	v_mul_f32_e32 v154, 0xbfb8aa3b, v154
	v_exp_f32_e32 v159, v159
	v_exp_f32_e32 v160, v160
	s_waitcnt lgkmcnt(0)
	v_add_f32_e32 v143, v142, v143
	ds_bpermute_b32 v156, v8, v143
	v_rcp_f32_e32 v142, v151
	v_exp_f32_e32 v150, v155
	v_exp_f32_e32 v158, v158
	v_exp_f32_e32 v149, v154
	s_waitcnt lgkmcnt(0)
	v_add_f32_e32 v151, v143, v156
	ds_bpermute_b32 v156, v9, v151
	v_add_f32_e32 v152, 1.0, v157
	v_add_f32_e32 v157, 1.0, v148
	v_rcp_f32_e32 v148, v152
	v_add_f32_e32 v154, 1.0, v159
	s_waitcnt lgkmcnt(0)
	v_add_f32_e32 v151, v151, v156
	v_fmamk_f32 v151, v151, 0x3c000000, v201
	v_rsq_f32_e32 v152, v151
	v_add_f32_e32 v155, 1.0, v160
	v_add_f32_e32 v159, 1.0, v150
	v_add_f32_e32 v153, 1.0, v158
	v_add_f32_e32 v158, 1.0, v149
	v_rcp_f32_e32 v149, v154
	v_rcp_f32_e32 v150, v155
	v_rcp_f32_e32 v154, v157
	v_rcp_f32_e32 v155, v159
	v_rcp_f32_e32 v143, v153
	v_rcp_f32_e32 v151, v158
	v_pk_mul_f32 v[132:133], v[152:153], v[132:133] op_sel_hi:[0,1]
	v_pk_mul_f32 v[136:137], v[152:153], v[136:137] op_sel_hi:[0,1]
	v_pk_mul_f32 v[130:131], v[152:153], v[130:131] op_sel_hi:[0,1]
	v_pk_mul_f32 v[138:139], v[152:153], v[138:139] op_sel_hi:[0,1]
	v_pk_mul_f32 v[132:133], v[140:141], v[132:133]
	v_pk_mul_f32 v[136:137], v[144:145], v[136:137]
	v_pk_mul_f32 v[130:131], v[134:135], v[130:131]
	v_pk_mul_f32 v[134:135], v[146:147], v[138:139]
	v_pk_mul_f32 v[132:133], v[148:149], v[132:133]
	v_pk_mul_f32 v[136:137], v[154:155], v[136:137]
	v_pk_mul_f32 v[130:131], v[142:143], v[130:131]
	v_pk_mul_f32 v[134:135], v[150:151], v[134:135]
	v_and_b32_sdwa v140, v133, v220 dst_sel:DWORD dst_unused:UNUSED_PAD src0_sel:WORD_1 src1_sel:DWORD
	v_and_b32_sdwa v141, v132, v220 dst_sel:DWORD dst_unused:UNUSED_PAD src0_sel:WORD_1 src1_sel:DWORD
	v_and_b32_sdwa v144, v137, v220 dst_sel:DWORD dst_unused:UNUSED_PAD src0_sel:WORD_1 src1_sel:DWORD
	v_and_b32_sdwa v145, v136, v220 dst_sel:DWORD dst_unused:UNUSED_PAD src0_sel:WORD_1 src1_sel:DWORD
	v_and_b32_sdwa v138, v131, v220 dst_sel:DWORD dst_unused:UNUSED_PAD src0_sel:WORD_1 src1_sel:DWORD
	v_and_b32_sdwa v139, v130, v220 dst_sel:DWORD dst_unused:UNUSED_PAD src0_sel:WORD_1 src1_sel:DWORD
	v_and_b32_sdwa v142, v135, v220 dst_sel:DWORD dst_unused:UNUSED_PAD src0_sel:WORD_1 src1_sel:DWORD
	v_and_b32_sdwa v143, v134, v220 dst_sel:DWORD dst_unused:UNUSED_PAD src0_sel:WORD_1 src1_sel:DWORD
	v_add3_u32 v133, v133, v140, s72
	v_add3_u32 v132, v132, v141, s72
	v_add3_u32 v137, v137, v144, s72
	v_add3_u32 v136, v136, v145, s72
	v_add3_u32 v130, v130, v139, s72
	v_add3_u32 v131, v131, v138, s72
	v_add3_u32 v134, v134, v143, s72
	v_add3_u32 v135, v135, v142, s72
	v_and_b32_e32 v133, 0xffff0000, v133
	v_and_b32_e32 v132, 0xffff0000, v132
	v_and_b32_e32 v137, 0xffff0000, v137
	v_and_b32_e32 v136, 0xffff0000, v136
	v_or_b32_sdwa v131, v133, v131 dst_sel:DWORD dst_unused:UNUSED_PAD src0_sel:DWORD src1_sel:WORD_1
	v_or_b32_sdwa v130, v132, v130 dst_sel:DWORD dst_unused:UNUSED_PAD src0_sel:DWORD src1_sel:WORD_1
	v_or_b32_sdwa v133, v137, v135 dst_sel:DWORD dst_unused:UNUSED_PAD src0_sel:DWORD src1_sel:WORD_1
	v_or_b32_sdwa v132, v136, v134 dst_sel:DWORD dst_unused:UNUSED_PAD src0_sel:DWORD src1_sel:WORD_1
	global_store_dwordx4 v[174:175], v[130:133], off offset:-4096
	v_lshl_add_u64 v[4:5], v[174:175], 0, s[26:27]
	s_andn2_b64 exec, exec, s[14:15]
	s_cbranch_execnz .LBB0_33
	s_branch .LBB0_30
